# grid barrier: issue the L1 invalidate (buffer_inv sc1) right after the arrive atomic so it overlaps with the wait instead of following the release
# speedup vs baseline: 1.0151x; 1.0114x over previous
.Lxb_have:
	v_readfirstlane_b32 s10, v0
	v_readfirstlane_b32 s11, v1
	s_add_u32 s12, s6, s3
	s_addc_u32 s13, s7, 0
	v_mov_b32_e32 v2, 1
	s_add_i32 s101, s101, 1
	s_mul_i32 s10, s10, s101
	s_mul_i32 s11, s11, s101
	s_waitcnt lgkmcnt(0)
	global_atomic_add v3, v196, v2, s[12:13] offset:1024 sc0
	buffer_inv sc1
	v_readlane_b32 s8, v240, 0
	s_lshl_b32 s8, s8, 6
	s_add_u32 s8, s8, 0x4000
	s_add_u32 s14, s6, s8
	s_addc_u32 s15, s7, 0
	s_mov_b32 s9, 0
	s_waitcnt vmcnt(1)
	v_add_u32_e32 v3, 1, v3
	v_cmp_eq_u32_e32 vcc, s10, v3
	s_cbranch_vccz .Lxb_poll
	buffer_wbl2 sc1
	v_readlane_b32 s12, v240, 46
	v_readlane_b32 s13, v240, 47
	s_waitcnt vmcnt(0)
	s_nop 3
	global_atomic_add v3, v165, v2, s[12:13] sc0
	s_waitcnt vmcnt(0)
	v_add_u32_e32 v3, 1, v3
	v_cmp_eq_u32_e32 vcc, s11, v3
	s_cbranch_vccz .Lxb_poll
	s_add_u32 s12, s6, 0x4000
	s_addc_u32 s13, s7, 0
	s_mov_b64 exec, -1
	v_mbcnt_lo_u32_b32 v3, -1, 0
	v_mbcnt_hi_u32_b32 v3, -1, v3
	v_mov_b32_e32 v2, 1
	v_lshlrev_b32_e32 v3, 6, v3
	v_add_u32_e32 v4, 0x1000, v3
	v_add_u32_e32 v5, 0x2000, v3
	v_add_u32_e32 v6, 0x3000, v3
	global_atomic_add v3, v2, s[12:13]
	global_atomic_add v4, v2, s[12:13]
	global_atomic_add v5, v2, s[12:13]
	global_atomic_add v6, v2, s[12:13]
	s_waitcnt vmcnt(4)
	s_mov_b64 exec, 1
	s_branch .LBB0_463
.Lxb_poll:
	global_load_dword v3, v165, s[14:15] sc1
	s_add_i32 s9, s9, 1
	s_waitcnt vmcnt(0)
	v_cmp_gt_u32_e32 vcc, s101, v3
	s_cbranch_vccz .Lxb_done
	s_cmp_gt_u32 s9, 0x40000
	s_cbranch_scc1 .Lxb_done
	s_sleep 1
	s_branch .Lxb_poll
.Lxb_done:
	s_waitcnt vmcnt(0)
.LBB0_463:
	s_or_b64 exec, exec, s[4:5]
	s_mov_b64 s[4:5], 0
	s_waitcnt lgkmcnt(0)
	s_barrier
